# cvhost LDS-transpose: hosted stores issued after the loads (youngest), step-B wait relaxed to vmcnt(5/3/2) so store acks also get two tile steps
# baseline (speedup 1.0000x reference)
; #define GAS __attribute__((address_space(1)))
; __device__ __forceinline__ unsigned cvt_pk_bf16(float lo, float hi) { unsigned r; asm volatile("v_cvt_pk_bf16_f32 %0, %1, %2" : "=v"(r) : "v"(lo), "v"(hi)); return r; }
; template <int NB>
; __device__ __forceinline__ void p0_batch(int it0, int stride, int lane, const P0Ptrs& a) {
;     ...
;     for (int q = 0; q < NB; ++q) {
;         const float gs = d[q].gs; const bool hk = d[q].ks != nullptr;
;         const f32x4 t0 = hk ? s0[q] * gs : (f32x4){gs, gs, gs, gs}, t1 = hk ? s1[q] * gs : (f32x4){gs, gs, gs, gs};
; #pragma unroll
;         for (int i = 0; i < 4; ++i) { v[q][i] *= t0[i]; v[q][4 + i] *= t1[i]; }
;         if (d[q].dst) {
; #pragma unroll
;             for (int e = 0; e < 4; ++e) { u32x4 o; o.x = cvt_pk_bf16(v[q][0][e], v[q][1][e]); o.y = cvt_pk_bf16(v[q][2][e], v[q][3][e]); o.z = cvt_pk_bf16(v[q][4][e], v[q][5][e]); o.w = cvt_pk_bf16(v[q][6][e], v[q][7][e]);
;                 *(GAS u32x4*)(d[q].dst + (size_t)e * d[q].ldt) = o; } }
;     }
.Lcv_nomul:
	v_readfirstlane_b32 s98, v0
	v_and_b32_e32 v76, 63, v0
	v_lshrrev_b32_e32 v77, 2, v76
	v_and_b32_e32 v78, 3, v76
	s_lshr_b32 s98, s98, 6
	s_lshl_b32 s99, s98, 10
	s_cmp_lt_u32 s98, 6
	s_mov_b32 s98, 0x24c00
	s_cselect_b32 s98, 0x1e800, s98
	s_add_i32 s98, s98, s99
	v_lshlrev_b32_e32 v81, 8, v78
	v_lshl_add_u32 v81, v77, 2, v81
	v_add_u32_e32 v81, s98, v81
	v_lshl_add_u32 v82, v76, 4, s98
	v_lshlrev_b32_e32 v83, 3, v78
	v_mad_u32_u24 v83, v77, s91, v83
	ds_write_b32 v81, v238
	ds_write_b32 v81, v239 offset:64
	ds_write_b32 v81, v240 offset:128
	ds_write_b32 v81, v241 offset:192
	ds_read_b128 v[100:103], v82
	ds_write_b32 v81, v242
	ds_write_b32 v81, v243 offset:64
	ds_write_b32 v81, v244 offset:128
	ds_write_b32 v81, v245 offset:192
	ds_read_b128 v[104:107], v82
	s_lshl_b32 s98, s91, 4
	s_add_u32 s98, s92, s98
	s_addc_u32 s99, s93, 0
	s_waitcnt lgkmcnt(0)
	v_cvt_pk_bf16_f32 v100, v100, v101
	v_cvt_pk_bf16_f32 v101, v102, v103
	v_cvt_pk_bf16_f32 v104, v104, v105
	v_cvt_pk_bf16_f32 v105, v106, v107
	s_mov_b64 s[72:73], s[92:93]
	s_mov_b64 s[74:75], s[98:99]
	s_add_u32 s92, s92, 32
	s_addc_u32 s93, s93, 0

; #define GAS __attribute__((address_space(1)))
; __device__ __forceinline__ unsigned cvt_pk_bf16(float lo, float hi) { unsigned r; asm volatile("v_cvt_pk_bf16_f32 %0, %1, %2" : "=v"(r) : "v"(lo), "v"(hi)); return r; }
; template <int NB>
; __device__ __forceinline__ void p0_batch(int it0, int stride, int lane, const P0Ptrs& a) {
;     ...
;         if (d[q].dst) {
; #pragma unroll
;             for (int e = 0; e < 4; ++e) { u32x4 o; o.x = cvt_pk_bf16(v[q][0][e], v[q][1][e]); o.y = cvt_pk_bf16(v[q][2][e], v[q][3][e]); o.z = cvt_pk_bf16(v[q][4][e], v[q][5][e]); o.w = cvt_pk_bf16(v[q][6][e], v[q][7][e]);
;                 *(GAS u32x4*)(d[q].dst + (size_t)e * d[q].ldt) = o; } }
;     }
.Lcv_noload:
	s_cmp_eq_u32 s87, 0
	s_cbranch_scc1 .Lcv_nost
	global_store_dwordx2 v83, v[100:101], s[72:73]
	global_store_dwordx2 v83, v[104:105], s[74:75]
.Lcv_nost:
	s_and_b32 s98, s87, 3
	s_cmp_lg_u32 s98, 3
	s_cbranch_scc1 .Lcv_inc
	s_cmp_gt_u32 s87, 18
	s_cbranch_scc1 .Lcv_inc
	s_add_i32 s99, s32, 1
	s_movk_i32 s98, 0x78
	s_cmp_lt_u32 s99, 7
	s_cselect_b32 s98, 0x60, s98
	s_cmp_eq_u32 s99, 0
	s_cselect_b32 s98, 0x50, s98
	s_cselect_b32 s99, 0, 0x58
	s_load_dwordx2 s[88:89], s[100:101], s98
	s_cmp_eq_u32 s99, 0
	s_cbranch_scc0 .Lcv_s1b_s
	s_bfe_u32 s99, s2, 0x50003
	s_cmp_lt_u32 s99, 16
	s_cselect_b32 s99, 64, 0x48

.LBB0_764:
	s_add_i32 s98, s87, -2
	s_cmp_lt_u32 s98, 19
	s_cbranch_scc1 .Lcv_w5
	s_cmp_eq_u32 s87, 1
	s_cbranch_scc1 .Lcv_w3
	s_cmp_eq_u32 s87, 21
	s_cbranch_scc1 .Lcv_w2
	s_waitcnt vmcnt(0)
	s_branch .Lcv_wd
.Lcv_w5:
	s_waitcnt vmcnt(5)
	s_branch .Lcv_wd
.Lcv_w3:
	s_waitcnt vmcnt(3)
	s_branch .Lcv_wd
.Lcv_w2:
	s_waitcnt vmcnt(2)
